# NA item: rel-pos-bias table staging loops moved after the Q + tile-0 K/V load issue so their round trips overlap
# speedup vs baseline: 1.0007x; 1.0007x over previous
; __device__ __forceinline__ int v_st(int k, int c) { const int kk = (k & ~0xC) | ((k & 4) << 1) | ((k & 8) >> 1); return ((kk >> 3) * 4 + (c >> 5)) * 512 + ((kk & 7) * 32 + (c & 31)) * 2; }
; __device__ __forceinline__ int v_rd_base(int lane) { return ((lane & 3) << 3) | (((lane >> 2) & 3) << 6) | (((lane >> 4) & 1) << 5) | (((lane >> 5) & 1) << 8); }
; #define SLOAD(i, k0) do { sr_[i].vs0 = *reinterpret_cast<const bf16x8*>(&Vh[(long)((k0) + sr) * LDP + sc]); sr_[i].vs1 = *reinterpret_cast<const bf16x8*>(&Vh[(long)((k0) + 32 + sr) * LDP + sc]); \
;     sr_[i].ks0 = *reinterpret_cast<const bf16x8*>(&Kh[(long)((k0) + ksr) * LDP + ksc]); if (DK == 128) sr_[i].ks1 = *reinterpret_cast<const bf16x8*>(&Kh[(long)((k0) + 32 + ksr) * LDP + ksc]); } while (0)
; template <int DK, bool NA, bool QL, int SD> ...
;     ...
;   const bf16* Qw = Qb + (long)(wid * 32 + r32) * LDP + hi * 8;
; #pragma unroll
;   for (int d0 = 0; d0 < DK / 16; ++d0) { const bf16x8 qv = *reinterpret_cast<const bf16x8*>(Qw + d0 * 16); if (QL) *reinterpret_cast<bf16x8*>(ql + d0 * 1024) = qv; else qr[d0] = qv; }
;   const int sr = tid >> 4, sc = (tid & 15) * 8, vst0 = v_st(sr, sc), vst1 = v_st(32 + sr, sc);
;   const int ksr = DK == 128 ? sr : (tid >> 3), ksc = DK == 128 ? sc : (tid & 7) * 8;
;   const int vb0 = (int)(uintptr_t)V_lds + v_rd_base(lane);
;   struct { bf16x8 vs0, vs1, ks0, ks1; } sr_[SD];
;     ...
;   f32x16 pA0, pA1, pB0, pB1; float mnA, mnB, alA, alB; bf16x8 pa0, pa1, pa2, pa3;
;   constexpr int SE = 0, SO = SD - 1;
;   SLOAD(SE, 0); asm volatile("s_waitcnt vmcnt(0)" ::: "memory"); SWRITE(0, SE); __syncthreads();
; __global__ void __launch_bounds__(NTHR) mega_fwd(Params p) {
;     ...
;                     { const float* rsrc = p.na_rpb + (size_t)(l * 4 + h) * 465; float* rdst = (float*)((char*)lds + att::RPB_OFF); for (int e = tid; e < 465; e += NTHR) rdst[e] = rsrc[e]; }
.LBB0_382:
	v_mov_b32_e32 v36, v188
	v_readlane_b32 s0, v254, 57
	v_ashrrev_i32_e32 v0, 6, v36
	v_and_b32_e32 v38, 63, v36
	v_lshl_add_u32 v2, v0, 13, s0
	v_readlane_b32 s0, v253, 0
	v_and_b32_e32 v37, 31, v36
	v_lshlrev_b32_e32 v42, 4, v38
	v_readlane_b32 s1, v253, 1
	v_bfe_u32 v34, v36, 5, 1
	v_add_u32_e32 v147, v2, v42
	v_lshl_or_b32 v0, v0, 5, v37
	v_mov_b64_e32 v[2:3], s[0:1]
	s_movk_i32 s0, 0x2800
	v_mad_i64_i32 v[2:3], s[0:1], v0, s0, v[2:3]
	v_lshlrev_b32_e32 v0, 4, v34
	v_lshl_add_u64 v[6:7], v[2:3], 0, v[0:1]
	global_load_dwordx4 v[2:5], v[6:7], off
	global_load_dwordx4 v[44:47], v[6:7], off offset:32
	global_load_dwordx4 v[48:51], v[6:7], off offset:64
	global_load_dwordx4 v[52:55], v[6:7], off offset:96
	global_load_dwordx4 v[56:59], v[6:7], off offset:128
	global_load_dwordx4 v[60:63], v[6:7], off offset:160
	global_load_dwordx4 v[64:67], v[6:7], off offset:192
	global_load_dwordx4 v[68:71], v[6:7], off offset:224
	v_ashrrev_i32_e32 v39, 4, v36
	v_add_u32_e32 v20, 32, v39
	s_movk_i32 s4, 0x1400
	v_readlane_b32 s2, v253, 4
	v_readlane_b32 s3, v253, 5
	v_lshlrev_b32_e32 v35, 8, v37
	v_or_b32_e32 v43, 32, v0
	v_lshlrev_b32_e32 v6, 1, v20
	v_lshlrev_b32_e32 v116, 3, v36
	v_and_b32_e32 v116, 0x78, v116
	v_mad_i64_i32 v[96:97], s[0:1], v39, s4, 0
	v_or_b32_e32 v96, v96, v116
	v_lshlrev_b64 v[96:97], 1, v[96:97]
	v_mad_i64_i32 v[98:99], s[0:1], v20, s4, 0
	v_or_b32_e32 v98, v98, v116
	v_lshlrev_b64 v[98:99], 1, v[98:99]
	v_lshl_add_u64 v[100:101], s[2:3], 0, v[96:97]
	v_lshl_add_u64 v[104:105], s[2:3], 0, v[98:99]
	v_readlane_b32 s0, v253, 2
	v_readlane_b32 s1, v253, 3
	global_load_dwordx4 v[100:103], v[100:101], off
	global_load_dwordx4 v[104:107], v[104:105], off
	s_nop 1
	v_lshl_add_u64 v[108:109], s[0:1], 0, v[96:97]
	v_lshl_add_u64 v[112:113], s[0:1], 0, v[98:99]
	global_load_dwordx4 v[108:111], v[108:109], off
	global_load_dwordx4 v[112:115], v[112:113], off
	s_mov_b64 s[0:1], exec
	v_readlane_b32 s2, v255, 26
	v_readlane_b32 s3, v255, 27
	s_and_b64 s[2:3], s[0:1], s[2:3]
	s_mov_b64 exec, s[2:3]
	s_cbranch_execz .LNAstg_end
	s_mov_b64 s[4:5], -1
	v_mov_b32_e32 v12, v154
	v_mov_b32_e32 v10, v205
	s_mov_b64 s[2:3], exec
	v_readlane_b32 s6, v255, 42
	v_readlane_b32 s7, v255, 43
	s_and_b64 s[6:7], s[2:3], s[6:7]
	s_mov_b64 exec, s[6:7]
	s_cbranch_execz .LBB0_379
	v_readlane_b32 s6, v255, 38
	s_mov_b64 s[4:5], 0
	v_mov_b32_e32 v10, v203
	v_mov_b32_e32 v14, v206
	v_mov_b64_e32 v[12:13], v[154:155]
	v_readlane_b32 s7, v255, 39
.LBB0_375:
	v_ashrrev_i32_e32 v17, 31, v13
	v_mov_b32_e32 v16, v13
	v_ashrrev_i32_e32 v19, 31, v12
	v_mov_b32_e32 v18, v12
	v_lshl_add_u64 v[18:19], v[18:19], 2, s[6:7]
	v_lshl_add_u64 v[16:17], v[16:17], 2, s[6:7]
	global_load_dword v15, v[18:19], off
	s_nop 0
	global_load_dword v16, v[16:17], off
	v_add_u32_e32 v10, -2, v10
	v_add_u32_e32 v17, 0xfffff800, v14
	v_cmp_eq_u32_e32 vcc, 0, v10
	v_add_u32_e32 v13, 0x400, v13
	v_add_u32_e32 v12, 0x400, v12
	s_or_b64 s[4:5], vcc, s[4:5]
	s_waitcnt vmcnt(1)
	ds_write_b32 v17, v15
	s_waitcnt vmcnt(0)
	ds_write_b32 v14, v16
	v_add_u32_e32 v14, 0x1000, v14
	s_andn2_b64 exec, exec, s[4:5]
	s_cbranch_execnz .LBB0_375
	s_or_b64 exec, exec, s[4:5]
	s_mov_b64 s[4:5], 0
	s_mov_b64 s[6:7], exec
	v_readlane_b32 s8, v255, 44
	v_readlane_b32 s9, v255, 45
	s_and_b64 s[8:9], s[6:7], s[8:9]
	s_mov_b64 exec, s[8:9]
	s_mov_b64 s[4:5], exec
	v_lshlrev_b32_e32 v10, 2, v204
	s_or_b64 exec, exec, s[6:7]
	s_orn2_b64 s[4:5], s[4:5], exec
	v_mov_b32_e32 v12, v204
.LBB0_379:
	s_or_b64 exec, exec, s[2:3]
	s_and_b64 s[2:3], exec, s[4:5]
	s_mov_b64 s[6:7], 0x800
	s_mov_b64 exec, s[2:3]
	s_cbranch_execz .LNAstg_end
	v_readlane_b32 s2, v255, 46
	v_ashrrev_i32_e32 v13, 31, v12
	v_readlane_b32 s3, v255, 47
	v_add_u32_e32 v14, 0xfffffe00, v12
	s_nop 0
	v_lshl_add_u64 v[12:13], v[12:13], 2, s[2:3]
	v_readlane_b32 s2, v254, 56
	s_nop 1
	v_add_u32_e32 v10, s2, v10
	s_mov_b64 s[2:3], 0
.LBB0_381:
	global_load_dword v15, v[12:13], off
	v_add_u32_e32 v14, 0x200, v14
	s_movk_i32 s4, 0xffd0
	v_cmp_lt_i32_e32 vcc, s4, v14
	v_lshl_add_u64 v[12:13], v[12:13], 0, s[6:7]
	s_or_b64 s[2:3], vcc, s[2:3]
	s_waitcnt vmcnt(0)
	ds_write_b32 v10, v15
	v_add_u32_e32 v10, 0x800, v10
	s_andn2_b64 exec, exec, s[2:3]
	s_cbranch_execnz .LBB0_381
; __device__ __forceinline__ int crow(int r, int hi) { return (r & 3) + 8 * (r >> 2) + 4 * hi; }
; __device__ __forceinline__ int v_st(int k, int c) { const int kk = (k & ~0xC) | ((k & 4) << 1) | ((k & 8) >> 1); return ((kk >> 3) * 4 + (c >> 5)) * 512 + ((kk & 7) * 32 + (c & 31)) * 2; }
; template <int DK, bool QL>
; __device__ __forceinline__ void qkt(f32x16& p0, f32x16& p1, const bf16* Ks, const bf16x8* qr, const char* ql, int r32, int hi) {
;   p0 = f32x16{}; p1 = f32x16{};
; #pragma unroll
;   for (int d0 = 0; d0 < DK / 16; ++d0) { int cb = (d0 * 16 + hi * 8) * 2;
;     const bf16x8 qv = QL ? *reinterpret_cast<const bf16x8*>(ql + d0 * 1024) : qr[d0];
;     bf16x8 b0 = *reinterpret_cast<const bf16x8*>((const char*)Ks + kswz<DK>(r32, cb));
;     bf16x8 b1 = *reinterpret_cast<const bf16x8*>((const char*)Ks + kswz<DK>(32 + r32, cb));
;     p0 = __builtin_amdgcn_mfma_f32_32x32x16_bf16(b0, qv, p0, 0, 0, 0);
;     p1 = __builtin_amdgcn_mfma_f32_32x32x16_bf16(b1, qv, p1, 0, 0, 0); }
; }
; __device__ __forceinline__ void na_hook(f32x16& p0, f32x16& p1, int kr, int q_row, int q_col, int win_r, int win_c, const float* rpb, float inv_scale, int hi) {
;   const bool rowok = (kr >= win_r) && (kr < win_r + 8);
;   int ir = kr - q_row + 7; ir = ir < 0 ? 0 : (ir > 14 ? 14 : ir);
;   const float* rp = rpb + ir * 31;
; #pragma unroll
;   for (int r = 0; r < 16; ++r) {
;     const int kc = crow(r, hi);
;     { const bool ok = rowok && kc >= win_c && kc < win_c + 16; int ic = kc - q_col + 15; ic = ic < 0 ? 0 : (ic > 30 ? 30 : ic);
;       p0[r] = ok ? fmaf(rp[ic], inv_scale, p0[r]) : -1e30f; }
; template <int DK, bool NA, bool QL, int SD> ...
;     ...
;   const int sr = tid >> 4, sc = (tid & 15) * 8, vst0 = v_st(sr, sc), vst1 = v_st(32 + sr, sc);
;   const int ksr = DK == 128 ? sr : (tid >> 3), ksc = DK == 128 ? sc : (tid & 7) * 8;
;   const int vb0 = (int)(uintptr_t)V_lds + v_rd_base(lane);
;   struct { bf16x8 vs0, vs1, ks0, ks1; } sr_[SD];
;     ...
;   f32x16 pA0, pA1, pB0, pB1; float mnA, mnB, alA, alB; bf16x8 pa0, pa1, pa2, pa3;
;   constexpr int SE = 0, SO = SD - 1;
;   SLOAD(SE, 0); asm volatile("s_waitcnt vmcnt(0)" ::: "memory"); SWRITE(0, SE); __syncthreads();
;   qkt<DK, QL>(pA0, pA1, K_lds, qr, ql, r32, hi); HOOK(pA0, pA1, 0); partialSM(pA0, pA1, m_reg, mnA, alA, C, thrRaw);
.LNAstg_end:
	s_or_b64 exec, exec, s[0:1]
	s_movk_i32 s4, 0x1400
	v_readlane_b32 s2, v253, 4
	v_readlane_b32 s3, v253, 5
	v_readlane_b32 s0, v253, 2
	v_readlane_b32 s1, v253, 3
	s_waitcnt vmcnt(11)
	ds_write_b128 v147, v[2:5]
	s_waitcnt vmcnt(10)
	ds_write_b128 v147, v[44:47] offset:1024
	s_waitcnt vmcnt(9)
	ds_write_b128 v147, v[48:51] offset:2048
	s_waitcnt vmcnt(8)
	ds_write_b128 v147, v[52:55] offset:3072
	s_waitcnt vmcnt(7)
	ds_write_b128 v147, v[56:59] offset:4096
	s_waitcnt vmcnt(6)
	ds_write_b128 v147, v[60:63] offset:5120
	s_waitcnt vmcnt(5)
	ds_write_b128 v147, v[64:67] offset:6144
	s_waitcnt vmcnt(4)
	ds_write_b128 v147, v[68:71] offset:7168
	v_and_b32_e32 v3, 0xfffff0, v39
	v_lshlrev_b32_e32 v4, 1, v39
	v_lshlrev_b32_e32 v2, 3, v36
	v_and_or_b32 v3, v4, 8, v3
	v_and_b32_e32 v40, 0x78, v2
	v_lshrrev_b32_e32 v4, 1, v39
	v_lshrrev_b32_e32 v3, 1, v3
	v_bfe_u32 v2, v2, 5, 2
	v_and_b32_e32 v5, 3, v39
	v_or_b32_e32 v3, v3, v2
	v_and_or_b32 v4, v4, 4, v5
	v_lshlrev_b32_e32 v18, 1, v40
	v_lshlrev_b32_e32 v3, 9, v3
	v_lshlrev_b32_e32 v4, 6, v4
	v_and_b32_e32 v5, 48, v18
	v_or3_b32 v19, v3, v4, v5
	v_and_b32_e32 v3, 0xfffff0, v20
	v_and_or_b32 v3, v6, 8, v3
	v_lshrrev_b32_e32 v3, 1, v3
	v_or_b32_e32 v2, v3, v2
	v_lshlrev_b32_e32 v2, 9, v2
	v_or3_b32 v21, v2, v4, v5
	v_mad_i64_i32 v[2:3], s[0:1], v39, s4, 0
	v_or_b32_e32 v2, v2, v40
	v_lshlrev_b64 v[10:11], 1, v[2:3]
	v_lshl_add_u64 v[2:3], s[2:3], 0, v[10:11]
	v_mad_i64_i32 v[6:7], s[0:1], v20, s4, 0
	v_or_b32_e32 v6, v6, v40
	v_lshlrev_b64 v[14:15], 1, v[6:7]
	v_lshl_add_u64 v[6:7], s[2:3], 0, v[14:15]
	v_readlane_b32 s0, v253, 2
	v_readlane_b32 s1, v253, 3
	v_add_u32_e32 v152, 0, v19
	v_add_u32_e32 v153, 0, v21
	v_lshl_add_u64 v[10:11], s[0:1], 0, v[10:11]
	v_lshl_add_u64 v[14:15], s[0:1], 0, v[14:15]
	v_readlane_b32 s0, v255, 28
	s_waitcnt vmcnt(0)
	v_readlane_b32 s1, v255, 29
	s_waitcnt vmcnt(3)
	ds_write_b128 v152, v[100:103]
	v_lshlrev_b32_e32 v2, 8, v39
	v_and_b32_e32 v3, 0xf0, v36
	v_bitop3_b32 v2, v18, v2, v3 bitop3:0xde
	v_add_u32_e32 v156, 0, v2
	v_lshlrev_b32_e32 v2, 8, v20
	v_bitop3_b32 v2, v18, v2, v3 bitop3:0xde
	v_add_u32_e32 v157, 0, v2
	v_lshlrev_b32_e32 v2, 4, v36
	v_and_b32_e32 v41, 0xf0, v2
	s_waitcnt vmcnt(2)
	ds_write_b128 v153, v[104:107]
	v_bitop3_b32 v6, v0, v35, v41 bitop3:0xde
	v_add_u32_e32 v158, 0, v6
	s_waitcnt vmcnt(1)
	ds_write_b128 v156, v[108:111] offset:32768
	v_bitop3_b32 v43, v43, v35, v41 bitop3:0xde
	s_waitcnt vmcnt(0)
	ds_write_b128 v157, v[112:115] offset:32768
	s_waitcnt lgkmcnt(0)
	s_barrier
	ds_read_b128 v[2:5], v147
	ds_read_b128 v[6:9], v158 offset:32768
	ds_read_b128 v[10:13], v158 offset:40960
	s_waitcnt lgkmcnt(1)
	v_mfma_f32_32x32x16_bf16 v[18:33], v[6:9], v[2:5], 0
	v_add_u32_e32 v159, 0, v43
	ds_read_b128 v[44:47], v147 offset:1024
	ds_read_b128 v[48:51], v159 offset:32768
	ds_read_b128 v[52:55], v159 offset:40960
	v_or_b32_e32 v43, 64, v0
	v_bitop3_b32 v43, v43, v35, v41 bitop3:0xde
	v_add_u32_e32 v160, 0, v43
	v_or_b32_e32 v43, 0x60, v0
	s_waitcnt lgkmcnt(3)
	v_mfma_f32_32x32x16_bf16 v[2:17], v[10:13], v[2:5], 0
	v_bitop3_b32 v43, v43, v35, v41 bitop3:0xde
	v_add_u32_e32 v161, 0, v43
	v_or_b32_e32 v43, 0x80, v0
	v_bitop3_b32 v43, v43, v35, v41 bitop3:0xde
	v_add_u32_e32 v176, 0, v43
	v_or_b32_e32 v43, 0xa0, v0
	v_bitop3_b32 v43, v43, v35, v41 bitop3:0xde
	s_waitcnt lgkmcnt(1)
	v_mfma_f32_32x32x16_bf16 v[18:33], v[48:51], v[44:47], v[18:33]
	v_add_u32_e32 v177, 0, v43
	v_or_b32_e32 v43, 0xc0, v0
	v_bitop3_b32 v43, v43, v35, v41 bitop3:0xde
	v_add_u32_e32 v207, 0, v43
	v_or_b32_e32 v0, 0xe0, v0
	v_bitop3_b32 v0, v0, v35, v41 bitop3:0xde
	v_add_u32_e32 v208, 0, v0
	s_waitcnt lgkmcnt(0)
	v_mfma_f32_32x32x16_bf16 v[2:17], v[52:55], v[44:47], v[2:17]
	ds_read_b128 v[44:47], v147 offset:2048
	ds_read_b128 v[48:51], v160 offset:32768
	ds_read_b128 v[52:55], v160 offset:40960
	v_lshlrev_b32_e32 v0, 2, v34
	v_cmp_lt_u32_e64 s[2:3], v0, v182
	v_mov_b32_e32 v34, 0xf149f2ca
	v_sub_u32_e32 v41, v0, v181
	v_writelane_b32 v255, s2, 50
	s_waitcnt lgkmcnt(1)
	v_mfma_f32_32x32x16_bf16 v[18:33], v[48:51], v[44:47], v[18:33]
	v_mov_b32_e32 v43, 0xf149f2ca
	v_writelane_b32 v255, s3, 51
	s_nor_b64 s[2:3], s[0:1], s[2:3]
	s_waitcnt lgkmcnt(0)
	v_mfma_f32_32x32x16_bf16 v[2:17], v[52:55], v[44:47], v[2:17]
	ds_read_b128 v[44:47], v147 offset:3072
	ds_read_b128 v[48:51], v161 offset:32768
	ds_read_b128 v[52:55], v161 offset:40960
	s_waitcnt lgkmcnt(1)
	v_mfma_f32_32x32x16_bf16 v[18:33], v[48:51], v[44:47], v[18:33]
	s_waitcnt lgkmcnt(0)
	v_mfma_f32_32x32x16_bf16 v[2:17], v[52:55], v[44:47], v[2:17]
	ds_read_b128 v[44:47], v147 offset:4096
	ds_read_b128 v[48:51], v176 offset:32768
	ds_read_b128 v[52:55], v176 offset:40960
	s_waitcnt lgkmcnt(1)
	v_mfma_f32_32x32x16_bf16 v[18:33], v[48:51], v[44:47], v[18:33]
	s_waitcnt lgkmcnt(0)
	v_mfma_f32_32x32x16_bf16 v[2:17], v[52:55], v[44:47], v[2:17]
	ds_read_b128 v[44:47], v147 offset:5120
	ds_read_b128 v[48:51], v177 offset:32768
	ds_read_b128 v[52:55], v177 offset:40960
	s_waitcnt lgkmcnt(1)
	v_mfma_f32_32x32x16_bf16 v[18:33], v[48:51], v[44:47], v[18:33]
	s_waitcnt lgkmcnt(0)
	v_mfma_f32_32x32x16_bf16 v[2:17], v[52:55], v[44:47], v[2:17]
	ds_read_b128 v[44:47], v147 offset:6144
	ds_read_b128 v[48:51], v207 offset:32768
	ds_read_b128 v[52:55], v207 offset:40960
	s_waitcnt lgkmcnt(1)
	v_mfma_f32_32x32x16_bf16 v[18:33], v[48:51], v[44:47], v[18:33]
	s_waitcnt lgkmcnt(0)
	v_mfma_f32_32x32x16_bf16 v[2:17], v[52:55], v[44:47], v[2:17]
	ds_read_b128 v[44:47], v147 offset:7168
	ds_read_b128 v[48:51], v208 offset:32768
	ds_read_b128 v[52:55], v208 offset:40960
	s_waitcnt lgkmcnt(1)
	v_mfma_f32_32x32x16_bf16 v[18:33], v[48:51], v[44:47], v[18:33]
	s_waitcnt lgkmcnt(0)
	v_mfma_f32_32x32x16_bf16 v[2:17], v[52:55], v[44:47], v[2:17]
	s_and_saveexec_b64 s[0:1], s[2:3]
	s_cbranch_execz .LBB0_384
	v_sub_u32_e32 v35, v0, v181
	v_max_i32_e32 v35, -15, v35
	v_lshl_add_u32 v35, v35, 2, v183
	ds_read_b32 v35, v35 offset:928
	s_waitcnt lgkmcnt(0)
	s_nop 2
	v_fmamk_f32 v43, v35, 0x413504f3, v18
